# adaLN modulation GEMM (phase 0) moved to the f32 matrix core (v_mfma_f32_32x32x2_f32, f32 operands and accumulate, exact f32): silu(c) computed in registers, weight rows streamed through a rolling reg
# speedup vs baseline: 1.0128x; 1.0015x over previous
; #define LAS __attribute__((address_space(3)))
; __device__ __forceinline__ float fsilu(float x) { return x * fsigmoid(x); }
; __device__ __forceinline__ void phase_prep(const Params& p, LAS unsigned char* lds) {
;     ...
;         LAS float* sc = (LAS float*)(lds) + wave * (128 * 33);
;         for (int i = 0; i < 64; ++i) { const int idx = lane + 64 * i, kl = idx & 127, b = idx >> 7;
;             const float cv = (b < 16 ? p.in[2] : p.in[3])[(b & 15) * D + 128 * wave + kl];
;             sc[kl * 33 + b] = fsilu(cv); }
;         asm volatile("s_waitcnt lgkmcnt(0)" ::: "memory");
;         float acc[32];
; #pragma unroll
;         for (int b = 0; b < 32; ++b) acc[b] = 0.f;
;         const float* W = p.in[4] + (size_t)(128 * wave) * 9216 + item * 64 + lane;
;         for (int k = 0; k < 128; ++k) { const float wv = W[(size_t)k * 9216];
.LBB0_139:
	v_and_b32_e32 v108, 31, v36
	v_lshrrev_b32_e32 v109, 5, v36
	v_mov_b32_e32 v110, s12
	v_mov_b32_e32 v111, s13
	v_mov_b32_e32 v112, s14
	v_mov_b32_e32 v113, s15
	v_cmp_gt_u32_e32 vcc, 16, v108
	s_nop 1
	v_cndmask_b32_e32 v110, v112, v110, vcc
	v_cndmask_b32_e32 v111, v113, v111, vcc
	v_and_b32_e32 v112, 15, v108
	v_lshlrev_b32_e32 v112, 12, v112
	v_lshl_add_u32 v113, v129, 7, v109
	v_lshl_add_u32 v112, v113, 2, v112
	v_mov_b32_e32 v113, 0
	v_lshl_add_u64 v[110:111], v[110:111], 0, v[112:113]
	v_readfirstlane_b32 s52, v0
	v_readfirstlane_b32 s53, v1
	v_mul_u32_u24_e32 v114, 0x9000, v109
	v_lshl_add_u32 v114, v108, 2, v114
	s_lshl_b32 s54, s4, 2
	s_add_u32 s52, s52, s54
	s_addc_u32 s53, s53, 0
	global_load_dword v160, v114, s[52:53]
	global_load_dword v161, v114, s[52:53] offset:128
	s_add_u32 s52, s52, 0x12000
	s_addc_u32 s53, s53, 0
	global_load_dword v162, v114, s[52:53]
	global_load_dword v163, v114, s[52:53] offset:128
	s_add_u32 s52, s52, 0x12000
	s_addc_u32 s53, s53, 0
	global_load_dword v164, v114, s[52:53]
	global_load_dword v165, v114, s[52:53] offset:128
	s_add_u32 s52, s52, 0x12000
	s_addc_u32 s53, s53, 0
	global_load_dword v166, v114, s[52:53]
	global_load_dword v167, v114, s[52:53] offset:128
	s_add_u32 s52, s52, 0x12000
	s_addc_u32 s53, s53, 0
	global_load_dword v168, v114, s[52:53]
	global_load_dword v169, v114, s[52:53] offset:128
	s_add_u32 s52, s52, 0x12000
	s_addc_u32 s53, s53, 0
	global_load_dword v170, v114, s[52:53]
	global_load_dword v171, v114, s[52:53] offset:128
	s_add_u32 s52, s52, 0x12000
	s_addc_u32 s53, s53, 0
	global_load_dword v172, v114, s[52:53]
	global_load_dword v173, v114, s[52:53] offset:128
	s_add_u32 s52, s52, 0x12000
	s_addc_u32 s53, s53, 0
	global_load_dword v174, v114, s[52:53]
	global_load_dword v175, v114, s[52:53] offset:128
	s_add_u32 s52, s52, 0x12000
	s_addc_u32 s53, s53, 0
	global_load_dword v176, v114, s[52:53]
	global_load_dword v177, v114, s[52:53] offset:128
	s_add_u32 s52, s52, 0x12000
	s_addc_u32 s53, s53, 0
	global_load_dword v178, v114, s[52:53]
	global_load_dword v179, v114, s[52:53] offset:128
	s_add_u32 s52, s52, 0x12000
	s_addc_u32 s53, s53, 0
	global_load_dword v180, v114, s[52:53]
	global_load_dword v181, v114, s[52:53] offset:128
	s_add_u32 s52, s52, 0x12000
	s_addc_u32 s53, s53, 0
	global_load_dword v182, v114, s[52:53]
	global_load_dword v183, v114, s[52:53] offset:128
	s_add_u32 s52, s52, 0x12000
	s_addc_u32 s53, s53, 0
	global_load_dword v184, v114, s[52:53]
	global_load_dword v185, v114, s[52:53] offset:128
	s_add_u32 s52, s52, 0x12000
	s_addc_u32 s53, s53, 0
	global_load_dword v186, v114, s[52:53]
	global_load_dword v187, v114, s[52:53] offset:128
	s_add_u32 s52, s52, 0x12000
	s_addc_u32 s53, s53, 0
	global_load_dword v188, v114, s[52:53]
	global_load_dword v189, v114, s[52:53] offset:128
	s_add_u32 s52, s52, 0x12000
	s_addc_u32 s53, s53, 0
	global_load_dword v190, v114, s[52:53]
	global_load_dword v191, v114, s[52:53] offset:128
	s_add_u32 s52, s52, 0x12000
	s_addc_u32 s53, s53, 0
	global_load_dword v192, v114, s[52:53]
	global_load_dword v193, v114, s[52:53] offset:128
	s_add_u32 s52, s52, 0x12000
	s_addc_u32 s53, s53, 0
	global_load_dword v194, v114, s[52:53]
	global_load_dword v195, v114, s[52:53] offset:128
	s_add_u32 s52, s52, 0x12000
	s_addc_u32 s53, s53, 0
	global_load_dword v196, v114, s[52:53]
	global_load_dword v197, v114, s[52:53] offset:128
	s_add_u32 s52, s52, 0x12000
	s_addc_u32 s53, s53, 0
	global_load_dword v198, v114, s[52:53]
	global_load_dword v199, v114, s[52:53] offset:128
	s_add_u32 s52, s52, 0x12000
	s_addc_u32 s53, s53, 0
	global_load_dword v200, v114, s[52:53]
	global_load_dword v201, v114, s[52:53] offset:128
	s_add_u32 s52, s52, 0x12000
	s_addc_u32 s53, s53, 0
	global_load_dword v202, v114, s[52:53]
	global_load_dword v203, v114, s[52:53] offset:128
	s_add_u32 s52, s52, 0x12000
	s_addc_u32 s53, s53, 0
	global_load_dword v204, v114, s[52:53]
	global_load_dword v205, v114, s[52:53] offset:128
	s_add_u32 s52, s52, 0x12000
	s_addc_u32 s53, s53, 0
	global_load_dword v206, v114, s[52:53]
	global_load_dword v207, v114, s[52:53] offset:128
	s_add_u32 s52, s52, 0x12000
	s_addc_u32 s53, s53, 0
	global_load_dword v208, v114, s[52:53]
	global_load_dword v209, v114, s[52:53] offset:128
	s_add_u32 s52, s52, 0x12000
	s_addc_u32 s53, s53, 0
	global_load_dword v210, v114, s[52:53]
	global_load_dword v211, v114, s[52:53] offset:128
	s_add_u32 s52, s52, 0x12000
	s_addc_u32 s53, s53, 0
	global_load_dword v212, v114, s[52:53]
	global_load_dword v213, v114, s[52:53] offset:128
	s_add_u32 s52, s52, 0x12000
	s_addc_u32 s53, s53, 0
	global_load_dword v214, v114, s[52:53]
	global_load_dword v215, v114, s[52:53] offset:128
	s_add_u32 s52, s52, 0x12000
	s_addc_u32 s53, s53, 0
	global_load_dword v216, v114, s[52:53]
	global_load_dword v217, v114, s[52:53] offset:128
	s_add_u32 s52, s52, 0x12000
	s_addc_u32 s53, s53, 0
	global_load_dword v218, v114, s[52:53]
	global_load_dword v219, v114, s[52:53] offset:128
	s_add_u32 s52, s52, 0x12000
	s_addc_u32 s53, s53, 0
	global_load_dword v220, v114, s[52:53]
	global_load_dword v221, v114, s[52:53] offset:128
	s_add_u32 s52, s52, 0x12000
	s_addc_u32 s53, s53, 0
	global_load_dword v222, v114, s[52:53]
	global_load_dword v223, v114, s[52:53] offset:128
	s_add_u32 s52, s52, 0x12000
	s_addc_u32 s53, s53, 0
	global_load_dword v44, v[110:111], off
	global_load_dword v45, v[110:111], off offset:8
	global_load_dword v46, v[110:111], off offset:16
	global_load_dword v47, v[110:111], off offset:24
	global_load_dword v48, v[110:111], off offset:32
	global_load_dword v49, v[110:111], off offset:40
	global_load_dword v50, v[110:111], off offset:48
; __device__ __forceinline__ float fexp(float x) { return __builtin_amdgcn_exp2f(x * 1.4426950408889634f); }
; __device__ __forceinline__ float fsigmoid(float x) { return __builtin_amdgcn_rcpf(1.0f + fexp(-x)); }
; __device__ __forceinline__ float fsilu(float x) { return x * fsigmoid(x); }
; __device__ __forceinline__ void phase_prep(const Params& p, LAS unsigned char* lds) {
;     ...
;         for (int i = 0; i < 64; ++i) { const int idx = lane + 64 * i, kl = idx & 127, b = idx >> 7;
;             const float cv = (b < 16 ? p.in[2] : p.in[3])[(b & 15) * D + 128 * wave + kl];
;             sc[kl * 33 + b] = fsilu(cv); }
	global_load_dword v51, v[110:111], off offset:56
	global_load_dword v52, v[110:111], off offset:64
	global_load_dword v53, v[110:111], off offset:72
	global_load_dword v54, v[110:111], off offset:80
	global_load_dword v55, v[110:111], off offset:88
	global_load_dword v56, v[110:111], off offset:96
	global_load_dword v57, v[110:111], off offset:104
	global_load_dword v58, v[110:111], off offset:112
	global_load_dword v59, v[110:111], off offset:120
	global_load_dword v60, v[110:111], off offset:128
	global_load_dword v61, v[110:111], off offset:136
	global_load_dword v62, v[110:111], off offset:144
	global_load_dword v63, v[110:111], off offset:152
	global_load_dword v64, v[110:111], off offset:160
	global_load_dword v65, v[110:111], off offset:168
	global_load_dword v66, v[110:111], off offset:176
	global_load_dword v67, v[110:111], off offset:184
	global_load_dword v68, v[110:111], off offset:192
	global_load_dword v69, v[110:111], off offset:200
	global_load_dword v70, v[110:111], off offset:208
	global_load_dword v71, v[110:111], off offset:216
	global_load_dword v72, v[110:111], off offset:224
	global_load_dword v73, v[110:111], off offset:232
	global_load_dword v74, v[110:111], off offset:240
	global_load_dword v75, v[110:111], off offset:248
	global_load_dword v76, v[110:111], off offset:256
	global_load_dword v77, v[110:111], off offset:264
	global_load_dword v78, v[110:111], off offset:272
	global_load_dword v79, v[110:111], off offset:280
	global_load_dword v80, v[110:111], off offset:288
	global_load_dword v81, v[110:111], off offset:296
	global_load_dword v82, v[110:111], off offset:304
	global_load_dword v83, v[110:111], off offset:312
	global_load_dword v84, v[110:111], off offset:320
	global_load_dword v85, v[110:111], off offset:328
	global_load_dword v86, v[110:111], off offset:336
	global_load_dword v87, v[110:111], off offset:344
	global_load_dword v88, v[110:111], off offset:352
	global_load_dword v89, v[110:111], off offset:360
	global_load_dword v90, v[110:111], off offset:368
	global_load_dword v91, v[110:111], off offset:376
	global_load_dword v92, v[110:111], off offset:384
	global_load_dword v93, v[110:111], off offset:392
	global_load_dword v94, v[110:111], off offset:400
	global_load_dword v95, v[110:111], off offset:408
	global_load_dword v96, v[110:111], off offset:416
	global_load_dword v97, v[110:111], off offset:424
	global_load_dword v98, v[110:111], off offset:432
	global_load_dword v99, v[110:111], off offset:440
	global_load_dword v100, v[110:111], off offset:448
	global_load_dword v101, v[110:111], off offset:456
	global_load_dword v102, v[110:111], off offset:464
	global_load_dword v103, v[110:111], off offset:472
	global_load_dword v104, v[110:111], off offset:480
	global_load_dword v105, v[110:111], off offset:488
	global_load_dword v106, v[110:111], off offset:496
	global_load_dword v107, v[110:111], off offset:504
	v_mov_b64_e32 v[2:3], 0
	v_mov_b64_e32 v[4:5], 0
	v_mov_b64_e32 v[6:7], 0
	v_mov_b64_e32 v[8:9], 0
	v_mov_b64_e32 v[10:11], 0
	v_mov_b64_e32 v[12:13], 0
	v_mov_b64_e32 v[14:15], 0
	v_mov_b64_e32 v[16:17], 0
	v_mov_b64_e32 v[18:19], 0
	v_mov_b64_e32 v[20:21], 0
	v_mov_b64_e32 v[22:23], 0
	v_mov_b64_e32 v[24:25], 0
	v_mov_b64_e32 v[26:27], 0
	v_mov_b64_e32 v[28:29], 0
	v_mov_b64_e32 v[30:31], 0
	v_mov_b64_e32 v[32:33], 0
	s_waitcnt vmcnt(0)
	v_mul_f32_e32 v116, 0xbfb8aa3b, v44
	v_mul_f32_e32 v117, 0xbfb8aa3b, v45
	v_mul_f32_e32 v118, 0xbfb8aa3b, v46
	v_mul_f32_e32 v119, 0xbfb8aa3b, v47
	v_exp_f32_e32 v116, v116
	v_exp_f32_e32 v117, v117
	v_exp_f32_e32 v118, v118
	v_exp_f32_e32 v119, v119
	v_add_f32_e32 v116, 1.0, v116
	v_add_f32_e32 v117, 1.0, v117
	v_add_f32_e32 v118, 1.0, v118
	v_add_f32_e32 v119, 1.0, v119
	v_rcp_f32_e32 v116, v116
	v_rcp_f32_e32 v117, v117
	v_rcp_f32_e32 v118, v118
	v_rcp_f32_e32 v119, v119
	v_mul_f32_e32 v44, v44, v116
	v_mul_f32_e32 v45, v45, v117
	v_mul_f32_e32 v46, v46, v118
	v_mul_f32_e32 v47, v47, v119
	v_mul_f32_e32 v116, 0xbfb8aa3b, v48
	v_mul_f32_e32 v117, 0xbfb8aa3b, v49
	v_mul_f32_e32 v118, 0xbfb8aa3b, v50
	v_mul_f32_e32 v119, 0xbfb8aa3b, v51
	v_exp_f32_e32 v116, v116
	v_exp_f32_e32 v117, v117
	v_exp_f32_e32 v118, v118
	v_exp_f32_e32 v119, v119
	v_add_f32_e32 v116, 1.0, v116
	v_add_f32_e32 v117, 1.0, v117
	v_add_f32_e32 v118, 1.0, v118
	v_add_f32_e32 v119, 1.0, v119
	v_rcp_f32_e32 v116, v116
	v_rcp_f32_e32 v117, v117
	v_rcp_f32_e32 v118, v118
	v_rcp_f32_e32 v119, v119
	v_mul_f32_e32 v48, v48, v116
	v_mul_f32_e32 v49, v49, v117
	v_mul_f32_e32 v50, v50, v118
	v_mul_f32_e32 v51, v51, v119
	v_mul_f32_e32 v116, 0xbfb8aa3b, v52
	v_mul_f32_e32 v117, 0xbfb8aa3b, v53
	v_mul_f32_e32 v118, 0xbfb8aa3b, v54
	v_mul_f32_e32 v119, 0xbfb8aa3b, v55
	v_exp_f32_e32 v116, v116
	v_exp_f32_e32 v117, v117
	v_exp_f32_e32 v118, v118
	v_exp_f32_e32 v119, v119
	v_add_f32_e32 v116, 1.0, v116
	v_add_f32_e32 v117, 1.0, v117
	v_add_f32_e32 v118, 1.0, v118
	v_add_f32_e32 v119, 1.0, v119
	v_rcp_f32_e32 v116, v116
	v_rcp_f32_e32 v117, v117
	v_rcp_f32_e32 v118, v118
	v_rcp_f32_e32 v119, v119
	v_mul_f32_e32 v52, v52, v116
	v_mul_f32_e32 v53, v53, v117
	v_mul_f32_e32 v54, v54, v118
	v_mul_f32_e32 v55, v55, v119
	v_mul_f32_e32 v116, 0xbfb8aa3b, v56
	v_mul_f32_e32 v117, 0xbfb8aa3b, v57
	v_mul_f32_e32 v118, 0xbfb8aa3b, v58
	v_mul_f32_e32 v119, 0xbfb8aa3b, v59
	v_exp_f32_e32 v116, v116
	v_exp_f32_e32 v117, v117
	v_exp_f32_e32 v118, v118
	v_exp_f32_e32 v119, v119
	v_add_f32_e32 v116, 1.0, v116
	v_add_f32_e32 v117, 1.0, v117
	v_add_f32_e32 v118, 1.0, v118
	v_add_f32_e32 v119, 1.0, v119
	v_rcp_f32_e32 v116, v116
	v_rcp_f32_e32 v117, v117
	v_rcp_f32_e32 v118, v118
	v_rcp_f32_e32 v119, v119
; __device__ __forceinline__ float fexp(float x) { return __builtin_amdgcn_exp2f(x * 1.4426950408889634f); }
; __device__ __forceinline__ float fsigmoid(float x) { return __builtin_amdgcn_rcpf(1.0f + fexp(-x)); }
; __device__ __forceinline__ float fsilu(float x) { return x * fsigmoid(x); }
; __device__ __forceinline__ void phase_prep(const Params& p, LAS unsigned char* lds) {
;     ...
;         for (int i = 0; i < 64; ++i) { const int idx = lane + 64 * i, kl = idx & 127, b = idx >> 7;
;             const float cv = (b < 16 ? p.in[2] : p.in[3])[(b & 15) * D + 128 * wave + kl];
;             sc[kl * 33 + b] = fsilu(cv); }
	v_mul_f32_e32 v56, v56, v116
	v_mul_f32_e32 v57, v57, v117
	v_mul_f32_e32 v58, v58, v118
	v_mul_f32_e32 v59, v59, v119
	v_mul_f32_e32 v116, 0xbfb8aa3b, v60
	v_mul_f32_e32 v117, 0xbfb8aa3b, v61
	v_mul_f32_e32 v118, 0xbfb8aa3b, v62
	v_mul_f32_e32 v119, 0xbfb8aa3b, v63
	v_exp_f32_e32 v116, v116
	v_exp_f32_e32 v117, v117
	v_exp_f32_e32 v118, v118
	v_exp_f32_e32 v119, v119
	v_add_f32_e32 v116, 1.0, v116
	v_add_f32_e32 v117, 1.0, v117
	v_add_f32_e32 v118, 1.0, v118
	v_add_f32_e32 v119, 1.0, v119
	v_rcp_f32_e32 v116, v116
	v_rcp_f32_e32 v117, v117
	v_rcp_f32_e32 v118, v118
	v_rcp_f32_e32 v119, v119
	v_mul_f32_e32 v60, v60, v116
	v_mul_f32_e32 v61, v61, v117
	v_mul_f32_e32 v62, v62, v118
	v_mul_f32_e32 v63, v63, v119
	v_mul_f32_e32 v116, 0xbfb8aa3b, v64
	v_mul_f32_e32 v117, 0xbfb8aa3b, v65
	v_mul_f32_e32 v118, 0xbfb8aa3b, v66
	v_mul_f32_e32 v119, 0xbfb8aa3b, v67
	v_exp_f32_e32 v116, v116
	v_exp_f32_e32 v117, v117
	v_exp_f32_e32 v118, v118
	v_exp_f32_e32 v119, v119
	v_add_f32_e32 v116, 1.0, v116
	v_add_f32_e32 v117, 1.0, v117
	v_add_f32_e32 v118, 1.0, v118
	v_add_f32_e32 v119, 1.0, v119
	v_rcp_f32_e32 v116, v116
	v_rcp_f32_e32 v117, v117
	v_rcp_f32_e32 v118, v118
	v_rcp_f32_e32 v119, v119
	v_mul_f32_e32 v64, v64, v116
	v_mul_f32_e32 v65, v65, v117
	v_mul_f32_e32 v66, v66, v118
	v_mul_f32_e32 v67, v67, v119
	v_mul_f32_e32 v116, 0xbfb8aa3b, v68
	v_mul_f32_e32 v117, 0xbfb8aa3b, v69
	v_mul_f32_e32 v118, 0xbfb8aa3b, v70
	v_mul_f32_e32 v119, 0xbfb8aa3b, v71
	v_exp_f32_e32 v116, v116
	v_exp_f32_e32 v117, v117
	v_exp_f32_e32 v118, v118
	v_exp_f32_e32 v119, v119
	v_add_f32_e32 v116, 1.0, v116
	v_add_f32_e32 v117, 1.0, v117
	v_add_f32_e32 v118, 1.0, v118
	v_add_f32_e32 v119, 1.0, v119
	v_rcp_f32_e32 v116, v116
	v_rcp_f32_e32 v117, v117
	v_rcp_f32_e32 v118, v118
	v_rcp_f32_e32 v119, v119
	v_mul_f32_e32 v68, v68, v116
	v_mul_f32_e32 v69, v69, v117
	v_mul_f32_e32 v70, v70, v118
	v_mul_f32_e32 v71, v71, v119
	v_mul_f32_e32 v116, 0xbfb8aa3b, v72
	v_mul_f32_e32 v117, 0xbfb8aa3b, v73
	v_mul_f32_e32 v118, 0xbfb8aa3b, v74
	v_mul_f32_e32 v119, 0xbfb8aa3b, v75
	v_exp_f32_e32 v116, v116
	v_exp_f32_e32 v117, v117
	v_exp_f32_e32 v118, v118
	v_exp_f32_e32 v119, v119
	v_add_f32_e32 v116, 1.0, v116
	v_add_f32_e32 v117, 1.0, v117
	v_add_f32_e32 v118, 1.0, v118
	v_add_f32_e32 v119, 1.0, v119
	v_rcp_f32_e32 v116, v116
	v_rcp_f32_e32 v117, v117
	v_rcp_f32_e32 v118, v118
	v_rcp_f32_e32 v119, v119
	v_mul_f32_e32 v72, v72, v116
	v_mul_f32_e32 v73, v73, v117
	v_mul_f32_e32 v74, v74, v118
	v_mul_f32_e32 v75, v75, v119
	v_mul_f32_e32 v116, 0xbfb8aa3b, v76
	v_mul_f32_e32 v117, 0xbfb8aa3b, v77
	v_mul_f32_e32 v118, 0xbfb8aa3b, v78
	v_mul_f32_e32 v119, 0xbfb8aa3b, v79
	v_exp_f32_e32 v116, v116
	v_exp_f32_e32 v117, v117
	v_exp_f32_e32 v118, v118
	v_exp_f32_e32 v119, v119
	v_add_f32_e32 v116, 1.0, v116
	v_add_f32_e32 v117, 1.0, v117
	v_add_f32_e32 v118, 1.0, v118
	v_add_f32_e32 v119, 1.0, v119
	v_rcp_f32_e32 v116, v116
	v_rcp_f32_e32 v117, v117
	v_rcp_f32_e32 v118, v118
	v_rcp_f32_e32 v119, v119
	v_mul_f32_e32 v76, v76, v116
	v_mul_f32_e32 v77, v77, v117
	v_mul_f32_e32 v78, v78, v118
	v_mul_f32_e32 v79, v79, v119
	v_mul_f32_e32 v116, 0xbfb8aa3b, v80
	v_mul_f32_e32 v117, 0xbfb8aa3b, v81
	v_mul_f32_e32 v118, 0xbfb8aa3b, v82
	v_mul_f32_e32 v119, 0xbfb8aa3b, v83
	v_exp_f32_e32 v116, v116
	v_exp_f32_e32 v117, v117
	v_exp_f32_e32 v118, v118
	v_exp_f32_e32 v119, v119
	v_add_f32_e32 v116, 1.0, v116
	v_add_f32_e32 v117, 1.0, v117
	v_add_f32_e32 v118, 1.0, v118
	v_add_f32_e32 v119, 1.0, v119
	v_rcp_f32_e32 v116, v116
	v_rcp_f32_e32 v117, v117
	v_rcp_f32_e32 v118, v118
	v_rcp_f32_e32 v119, v119
	v_mul_f32_e32 v80, v80, v116
	v_mul_f32_e32 v81, v81, v117
	v_mul_f32_e32 v82, v82, v118
	v_mul_f32_e32 v83, v83, v119
	v_mul_f32_e32 v116, 0xbfb8aa3b, v84
	v_mul_f32_e32 v117, 0xbfb8aa3b, v85
	v_mul_f32_e32 v118, 0xbfb8aa3b, v86
	v_mul_f32_e32 v119, 0xbfb8aa3b, v87
	v_exp_f32_e32 v116, v116
	v_exp_f32_e32 v117, v117
	v_exp_f32_e32 v118, v118
	v_exp_f32_e32 v119, v119
	v_add_f32_e32 v116, 1.0, v116
	v_add_f32_e32 v117, 1.0, v117
	v_add_f32_e32 v118, 1.0, v118
	v_add_f32_e32 v119, 1.0, v119
	v_rcp_f32_e32 v116, v116
	v_rcp_f32_e32 v117, v117
	v_rcp_f32_e32 v118, v118
	v_rcp_f32_e32 v119, v119
	v_mul_f32_e32 v84, v84, v116
	v_mul_f32_e32 v85, v85, v117
	v_mul_f32_e32 v86, v86, v118
	v_mul_f32_e32 v87, v87, v119
	v_mul_f32_e32 v116, 0xbfb8aa3b, v88
	v_mul_f32_e32 v117, 0xbfb8aa3b, v89
	v_mul_f32_e32 v118, 0xbfb8aa3b, v90
	v_mul_f32_e32 v119, 0xbfb8aa3b, v91
	v_exp_f32_e32 v116, v116
	v_exp_f32_e32 v117, v117
	v_exp_f32_e32 v118, v118
	v_exp_f32_e32 v119, v119
	v_add_f32_e32 v116, 1.0, v116
	v_add_f32_e32 v117, 1.0, v117
	v_add_f32_e32 v118, 1.0, v118
	v_add_f32_e32 v119, 1.0, v119
	v_rcp_f32_e32 v116, v116
	v_rcp_f32_e32 v117, v117
	v_rcp_f32_e32 v118, v118
	v_rcp_f32_e32 v119, v119
	v_mul_f32_e32 v88, v88, v116
	v_mul_f32_e32 v89, v89, v117
	v_mul_f32_e32 v90, v90, v118
	v_mul_f32_e32 v91, v91, v119
	v_mul_f32_e32 v116, 0xbfb8aa3b, v92
	v_mul_f32_e32 v117, 0xbfb8aa3b, v93
	v_mul_f32_e32 v118, 0xbfb8aa3b, v94
	v_mul_f32_e32 v119, 0xbfb8aa3b, v95
	v_exp_f32_e32 v116, v116
	v_exp_f32_e32 v117, v117
	v_exp_f32_e32 v118, v118
	v_exp_f32_e32 v119, v119
	v_add_f32_e32 v116, 1.0, v116
	v_add_f32_e32 v117, 1.0, v117
	v_add_f32_e32 v118, 1.0, v118
	v_add_f32_e32 v119, 1.0, v119
	v_rcp_f32_e32 v116, v116
	v_rcp_f32_e32 v117, v117
	v_rcp_f32_e32 v118, v118
	v_rcp_f32_e32 v119, v119
	v_mul_f32_e32 v92, v92, v116
	v_mul_f32_e32 v93, v93, v117
	v_mul_f32_e32 v94, v94, v118
	v_mul_f32_e32 v95, v95, v119
	v_mul_f32_e32 v116, 0xbfb8aa3b, v96
	v_mul_f32_e32 v117, 0xbfb8aa3b, v97
	v_mul_f32_e32 v118, 0xbfb8aa3b, v98
; __device__ __forceinline__ void phase_prep(const Params& p, LAS unsigned char* lds) {
;     ...
;         for (int k = 0; k < 128; ++k) { const float wv = W[(size_t)k * 9216];
; #pragma unroll
;             for (int b = 0; b < 32; ++b) acc[b] += sc[k * 33 + b] * wv; }
	v_mul_f32_e32 v119, 0xbfb8aa3b, v99
	v_exp_f32_e32 v116, v116
	v_exp_f32_e32 v117, v117
	v_exp_f32_e32 v118, v118
	v_exp_f32_e32 v119, v119
	v_add_f32_e32 v116, 1.0, v116
	v_add_f32_e32 v117, 1.0, v117
	v_add_f32_e32 v118, 1.0, v118
	v_add_f32_e32 v119, 1.0, v119
	v_rcp_f32_e32 v116, v116
	v_rcp_f32_e32 v117, v117
	v_rcp_f32_e32 v118, v118
	v_rcp_f32_e32 v119, v119
	v_mul_f32_e32 v96, v96, v116
	v_mul_f32_e32 v97, v97, v117
	v_mul_f32_e32 v98, v98, v118
	v_mul_f32_e32 v99, v99, v119
	v_mul_f32_e32 v116, 0xbfb8aa3b, v100
	v_mul_f32_e32 v117, 0xbfb8aa3b, v101
	v_mul_f32_e32 v118, 0xbfb8aa3b, v102
	v_mul_f32_e32 v119, 0xbfb8aa3b, v103
	v_exp_f32_e32 v116, v116
	v_exp_f32_e32 v117, v117
	v_exp_f32_e32 v118, v118
	v_exp_f32_e32 v119, v119
	v_add_f32_e32 v116, 1.0, v116
	v_add_f32_e32 v117, 1.0, v117
	v_add_f32_e32 v118, 1.0, v118
	v_add_f32_e32 v119, 1.0, v119
	v_rcp_f32_e32 v116, v116
	v_rcp_f32_e32 v117, v117
	v_rcp_f32_e32 v118, v118
	v_rcp_f32_e32 v119, v119
	v_mul_f32_e32 v100, v100, v116
	v_mul_f32_e32 v101, v101, v117
	v_mul_f32_e32 v102, v102, v118
	v_mul_f32_e32 v103, v103, v119
	v_mul_f32_e32 v116, 0xbfb8aa3b, v104
	v_mul_f32_e32 v117, 0xbfb8aa3b, v105
	v_mul_f32_e32 v118, 0xbfb8aa3b, v106
	v_mul_f32_e32 v119, 0xbfb8aa3b, v107
	v_exp_f32_e32 v116, v116
	v_exp_f32_e32 v117, v117
	v_exp_f32_e32 v118, v118
	v_exp_f32_e32 v119, v119
	v_add_f32_e32 v116, 1.0, v116
	v_add_f32_e32 v117, 1.0, v117
	v_add_f32_e32 v118, 1.0, v118
	v_add_f32_e32 v119, 1.0, v119
	v_rcp_f32_e32 v116, v116
	v_rcp_f32_e32 v117, v117
	v_rcp_f32_e32 v118, v118
	v_rcp_f32_e32 v119, v119
	v_mul_f32_e32 v104, v104, v116
	v_mul_f32_e32 v105, v105, v117
	v_mul_f32_e32 v106, v106, v118
	v_mul_f32_e32 v107, v107, v119
	s_nop 1
	v_mfma_f32_32x32x2_f32 v[2:17], v44, v160, v[2:17]
	v_mfma_f32_32x32x2_f32 v[18:33], v44, v161, v[18:33]
	global_load_dword v160, v114, s[52:53]
	global_load_dword v161, v114, s[52:53] offset:128
	s_add_u32 s52, s52, 0x12000
	s_addc_u32 s53, s53, 0
	v_mfma_f32_32x32x2_f32 v[2:17], v45, v162, v[2:17]
	v_mfma_f32_32x32x2_f32 v[18:33], v45, v163, v[18:33]
	global_load_dword v162, v114, s[52:53]
	global_load_dword v163, v114, s[52:53] offset:128
	s_add_u32 s52, s52, 0x12000
	s_addc_u32 s53, s53, 0
	v_mfma_f32_32x32x2_f32 v[2:17], v46, v164, v[2:17]
	v_mfma_f32_32x32x2_f32 v[18:33], v46, v165, v[18:33]
	global_load_dword v164, v114, s[52:53]
	global_load_dword v165, v114, s[52:53] offset:128
	s_add_u32 s52, s52, 0x12000
	s_addc_u32 s53, s53, 0
	v_mfma_f32_32x32x2_f32 v[2:17], v47, v166, v[2:17]
	v_mfma_f32_32x32x2_f32 v[18:33], v47, v167, v[18:33]
	global_load_dword v166, v114, s[52:53]
	global_load_dword v167, v114, s[52:53] offset:128
	s_add_u32 s52, s52, 0x12000
	s_addc_u32 s53, s53, 0
	v_mfma_f32_32x32x2_f32 v[2:17], v48, v168, v[2:17]
	v_mfma_f32_32x32x2_f32 v[18:33], v48, v169, v[18:33]
	global_load_dword v168, v114, s[52:53]
	global_load_dword v169, v114, s[52:53] offset:128
	s_add_u32 s52, s52, 0x12000
	s_addc_u32 s53, s53, 0
	v_mfma_f32_32x32x2_f32 v[2:17], v49, v170, v[2:17]
	v_mfma_f32_32x32x2_f32 v[18:33], v49, v171, v[18:33]
	global_load_dword v170, v114, s[52:53]
	global_load_dword v171, v114, s[52:53] offset:128
	s_add_u32 s52, s52, 0x12000
	s_addc_u32 s53, s53, 0
	v_mfma_f32_32x32x2_f32 v[2:17], v50, v172, v[2:17]
	v_mfma_f32_32x32x2_f32 v[18:33], v50, v173, v[18:33]
	global_load_dword v172, v114, s[52:53]
	global_load_dword v173, v114, s[52:53] offset:128
	s_add_u32 s52, s52, 0x12000
	s_addc_u32 s53, s53, 0
	v_mfma_f32_32x32x2_f32 v[2:17], v51, v174, v[2:17]
	v_mfma_f32_32x32x2_f32 v[18:33], v51, v175, v[18:33]
	global_load_dword v174, v114, s[52:53]
	global_load_dword v175, v114, s[52:53] offset:128
	s_add_u32 s52, s52, 0x12000
	s_addc_u32 s53, s53, 0
	v_mfma_f32_32x32x2_f32 v[2:17], v52, v176, v[2:17]
	v_mfma_f32_32x32x2_f32 v[18:33], v52, v177, v[18:33]
	global_load_dword v176, v114, s[52:53]
	global_load_dword v177, v114, s[52:53] offset:128
	s_add_u32 s52, s52, 0x12000
	s_addc_u32 s53, s53, 0
	v_mfma_f32_32x32x2_f32 v[2:17], v53, v178, v[2:17]
	v_mfma_f32_32x32x2_f32 v[18:33], v53, v179, v[18:33]
	global_load_dword v178, v114, s[52:53]
	global_load_dword v179, v114, s[52:53] offset:128
	s_add_u32 s52, s52, 0x12000
	s_addc_u32 s53, s53, 0
	v_mfma_f32_32x32x2_f32 v[2:17], v54, v180, v[2:17]
	v_mfma_f32_32x32x2_f32 v[18:33], v54, v181, v[18:33]
	global_load_dword v180, v114, s[52:53]
	global_load_dword v181, v114, s[52:53] offset:128
	s_add_u32 s52, s52, 0x12000
	s_addc_u32 s53, s53, 0
	v_mfma_f32_32x32x2_f32 v[2:17], v55, v182, v[2:17]
	v_mfma_f32_32x32x2_f32 v[18:33], v55, v183, v[18:33]
	global_load_dword v182, v114, s[52:53]
	global_load_dword v183, v114, s[52:53] offset:128
	s_add_u32 s52, s52, 0x12000
	s_addc_u32 s53, s53, 0
	v_mfma_f32_32x32x2_f32 v[2:17], v56, v184, v[2:17]
	v_mfma_f32_32x32x2_f32 v[18:33], v56, v185, v[18:33]
	global_load_dword v184, v114, s[52:53]
	global_load_dword v185, v114, s[52:53] offset:128
	s_add_u32 s52, s52, 0x12000
	s_addc_u32 s53, s53, 0
	v_mfma_f32_32x32x2_f32 v[2:17], v57, v186, v[2:17]
	v_mfma_f32_32x32x2_f32 v[18:33], v57, v187, v[18:33]
	global_load_dword v186, v114, s[52:53]
	global_load_dword v187, v114, s[52:53] offset:128
	s_add_u32 s52, s52, 0x12000
	s_addc_u32 s53, s53, 0
	v_mfma_f32_32x32x2_f32 v[2:17], v58, v188, v[2:17]
	v_mfma_f32_32x32x2_f32 v[18:33], v58, v189, v[18:33]
	global_load_dword v188, v114, s[52:53]
	global_load_dword v189, v114, s[52:53] offset:128
	s_add_u32 s52, s52, 0x12000
	s_addc_u32 s53, s53, 0
	v_mfma_f32_32x32x2_f32 v[2:17], v59, v190, v[2:17]
	v_mfma_f32_32x32x2_f32 v[18:33], v59, v191, v[18:33]
	global_load_dword v190, v114, s[52:53]
; __device__ __forceinline__ void phase_prep(const Params& p, LAS unsigned char* lds) {
;     ...
;         for (int k = 0; k < 128; ++k) { const float wv = W[(size_t)k * 9216];
; #pragma unroll
;             for (int b = 0; b < 32; ++b) acc[b] += sc[k * 33 + b] * wv; }
	global_load_dword v191, v114, s[52:53] offset:128
	s_add_u32 s52, s52, 0x12000
	s_addc_u32 s53, s53, 0
	v_mfma_f32_32x32x2_f32 v[2:17], v60, v192, v[2:17]
	v_mfma_f32_32x32x2_f32 v[18:33], v60, v193, v[18:33]
	global_load_dword v192, v114, s[52:53]
	global_load_dword v193, v114, s[52:53] offset:128
	s_add_u32 s52, s52, 0x12000
	s_addc_u32 s53, s53, 0
	v_mfma_f32_32x32x2_f32 v[2:17], v61, v194, v[2:17]
	v_mfma_f32_32x32x2_f32 v[18:33], v61, v195, v[18:33]
	global_load_dword v194, v114, s[52:53]
	global_load_dword v195, v114, s[52:53] offset:128
	s_add_u32 s52, s52, 0x12000
	s_addc_u32 s53, s53, 0
	v_mfma_f32_32x32x2_f32 v[2:17], v62, v196, v[2:17]
	v_mfma_f32_32x32x2_f32 v[18:33], v62, v197, v[18:33]
	global_load_dword v196, v114, s[52:53]
	global_load_dword v197, v114, s[52:53] offset:128
	s_add_u32 s52, s52, 0x12000
	s_addc_u32 s53, s53, 0
	v_mfma_f32_32x32x2_f32 v[2:17], v63, v198, v[2:17]
	v_mfma_f32_32x32x2_f32 v[18:33], v63, v199, v[18:33]
	global_load_dword v198, v114, s[52:53]
	global_load_dword v199, v114, s[52:53] offset:128
	s_add_u32 s52, s52, 0x12000
	s_addc_u32 s53, s53, 0
	v_mfma_f32_32x32x2_f32 v[2:17], v64, v200, v[2:17]
	v_mfma_f32_32x32x2_f32 v[18:33], v64, v201, v[18:33]
	global_load_dword v200, v114, s[52:53]
	global_load_dword v201, v114, s[52:53] offset:128
	s_add_u32 s52, s52, 0x12000
	s_addc_u32 s53, s53, 0
	v_mfma_f32_32x32x2_f32 v[2:17], v65, v202, v[2:17]
	v_mfma_f32_32x32x2_f32 v[18:33], v65, v203, v[18:33]
	global_load_dword v202, v114, s[52:53]
	global_load_dword v203, v114, s[52:53] offset:128
	s_add_u32 s52, s52, 0x12000
	s_addc_u32 s53, s53, 0
	v_mfma_f32_32x32x2_f32 v[2:17], v66, v204, v[2:17]
	v_mfma_f32_32x32x2_f32 v[18:33], v66, v205, v[18:33]
	global_load_dword v204, v114, s[52:53]
	global_load_dword v205, v114, s[52:53] offset:128
	s_add_u32 s52, s52, 0x12000
	s_addc_u32 s53, s53, 0
	v_mfma_f32_32x32x2_f32 v[2:17], v67, v206, v[2:17]
	v_mfma_f32_32x32x2_f32 v[18:33], v67, v207, v[18:33]
	global_load_dword v206, v114, s[52:53]
	global_load_dword v207, v114, s[52:53] offset:128
	s_add_u32 s52, s52, 0x12000
	s_addc_u32 s53, s53, 0
	v_mfma_f32_32x32x2_f32 v[2:17], v68, v208, v[2:17]
	v_mfma_f32_32x32x2_f32 v[18:33], v68, v209, v[18:33]
	global_load_dword v208, v114, s[52:53]
	global_load_dword v209, v114, s[52:53] offset:128
	s_add_u32 s52, s52, 0x12000
	s_addc_u32 s53, s53, 0
	v_mfma_f32_32x32x2_f32 v[2:17], v69, v210, v[2:17]
	v_mfma_f32_32x32x2_f32 v[18:33], v69, v211, v[18:33]
	global_load_dword v210, v114, s[52:53]
	global_load_dword v211, v114, s[52:53] offset:128
	s_add_u32 s52, s52, 0x12000
	s_addc_u32 s53, s53, 0
	v_mfma_f32_32x32x2_f32 v[2:17], v70, v212, v[2:17]
	v_mfma_f32_32x32x2_f32 v[18:33], v70, v213, v[18:33]
	global_load_dword v212, v114, s[52:53]
	global_load_dword v213, v114, s[52:53] offset:128
	s_add_u32 s52, s52, 0x12000
	s_addc_u32 s53, s53, 0
	v_mfma_f32_32x32x2_f32 v[2:17], v71, v214, v[2:17]
	v_mfma_f32_32x32x2_f32 v[18:33], v71, v215, v[18:33]
	global_load_dword v214, v114, s[52:53]
	global_load_dword v215, v114, s[52:53] offset:128
	s_add_u32 s52, s52, 0x12000
	s_addc_u32 s53, s53, 0
	v_mfma_f32_32x32x2_f32 v[2:17], v72, v216, v[2:17]
	v_mfma_f32_32x32x2_f32 v[18:33], v72, v217, v[18:33]
	global_load_dword v216, v114, s[52:53]
	global_load_dword v217, v114, s[52:53] offset:128
	s_add_u32 s52, s52, 0x12000
	s_addc_u32 s53, s53, 0
	v_mfma_f32_32x32x2_f32 v[2:17], v73, v218, v[2:17]
	v_mfma_f32_32x32x2_f32 v[18:33], v73, v219, v[18:33]
	global_load_dword v218, v114, s[52:53]
	global_load_dword v219, v114, s[52:53] offset:128
	s_add_u32 s52, s52, 0x12000
	s_addc_u32 s53, s53, 0
	v_mfma_f32_32x32x2_f32 v[2:17], v74, v220, v[2:17]
	v_mfma_f32_32x32x2_f32 v[18:33], v74, v221, v[18:33]
	global_load_dword v220, v114, s[52:53]
	global_load_dword v221, v114, s[52:53] offset:128
	s_add_u32 s52, s52, 0x12000
	s_addc_u32 s53, s53, 0
	v_mfma_f32_32x32x2_f32 v[2:17], v75, v222, v[2:17]
	v_mfma_f32_32x32x2_f32 v[18:33], v75, v223, v[18:33]
	global_load_dword v222, v114, s[52:53]
	global_load_dword v223, v114, s[52:53] offset:128
	s_add_u32 s52, s52, 0x12000
	s_addc_u32 s53, s53, 0
	s_waitcnt vmcnt(62)
	v_mfma_f32_32x32x2_f32 v[2:17], v76, v160, v[2:17]
	v_mfma_f32_32x32x2_f32 v[18:33], v76, v161, v[18:33]
	s_waitcnt vmcnt(60)
	v_mfma_f32_32x32x2_f32 v[2:17], v77, v162, v[2:17]
	v_mfma_f32_32x32x2_f32 v[18:33], v77, v163, v[18:33]
	s_waitcnt vmcnt(58)
	v_mfma_f32_32x32x2_f32 v[2:17], v78, v164, v[2:17]
	v_mfma_f32_32x32x2_f32 v[18:33], v78, v165, v[18:33]
	s_waitcnt vmcnt(56)
	v_mfma_f32_32x32x2_f32 v[2:17], v79, v166, v[2:17]
	v_mfma_f32_32x32x2_f32 v[18:33], v79, v167, v[18:33]
	s_waitcnt vmcnt(54)
	v_mfma_f32_32x32x2_f32 v[2:17], v80, v168, v[2:17]
	v_mfma_f32_32x32x2_f32 v[18:33], v80, v169, v[18:33]
	s_waitcnt vmcnt(52)
	v_mfma_f32_32x32x2_f32 v[2:17], v81, v170, v[2:17]
	v_mfma_f32_32x32x2_f32 v[18:33], v81, v171, v[18:33]
	s_waitcnt vmcnt(50)
; #define LAS __attribute__((address_space(3)))
; __device__ __forceinline__ void phase_prep(const Params& p, LAS unsigned char* lds) {
;     ...
;         for (int k = 0; k < 128; ++k) { const float wv = W[(size_t)k * 9216];
; #pragma unroll
;             for (int b = 0; b < 32; ++b) acc[b] += sc[k * 33 + b] * wv; }
;         __syncthreads();
;         LAS float* red = (LAS float*)(lds);
; #pragma unroll
;         for (int b = 0; b < 32; ++b) red[(wave * 32 + b) * 64 + lane] = acc[b];
;         __syncthreads();
	v_mfma_f32_32x32x2_f32 v[2:17], v82, v172, v[2:17]
	v_mfma_f32_32x32x2_f32 v[18:33], v82, v173, v[18:33]
	s_waitcnt vmcnt(48)
	v_mfma_f32_32x32x2_f32 v[2:17], v83, v174, v[2:17]
	v_mfma_f32_32x32x2_f32 v[18:33], v83, v175, v[18:33]
	s_waitcnt vmcnt(46)
	v_mfma_f32_32x32x2_f32 v[2:17], v84, v176, v[2:17]
	v_mfma_f32_32x32x2_f32 v[18:33], v84, v177, v[18:33]
	s_waitcnt vmcnt(44)
	v_mfma_f32_32x32x2_f32 v[2:17], v85, v178, v[2:17]
	v_mfma_f32_32x32x2_f32 v[18:33], v85, v179, v[18:33]
	s_waitcnt vmcnt(42)
	v_mfma_f32_32x32x2_f32 v[2:17], v86, v180, v[2:17]
	v_mfma_f32_32x32x2_f32 v[18:33], v86, v181, v[18:33]
	s_waitcnt vmcnt(40)
	v_mfma_f32_32x32x2_f32 v[2:17], v87, v182, v[2:17]
	v_mfma_f32_32x32x2_f32 v[18:33], v87, v183, v[18:33]
	s_waitcnt vmcnt(38)
	v_mfma_f32_32x32x2_f32 v[2:17], v88, v184, v[2:17]
	v_mfma_f32_32x32x2_f32 v[18:33], v88, v185, v[18:33]
	s_waitcnt vmcnt(36)
	v_mfma_f32_32x32x2_f32 v[2:17], v89, v186, v[2:17]
	v_mfma_f32_32x32x2_f32 v[18:33], v89, v187, v[18:33]
	s_waitcnt vmcnt(34)
	v_mfma_f32_32x32x2_f32 v[2:17], v90, v188, v[2:17]
	v_mfma_f32_32x32x2_f32 v[18:33], v90, v189, v[18:33]
	s_waitcnt vmcnt(32)
	v_mfma_f32_32x32x2_f32 v[2:17], v91, v190, v[2:17]
	v_mfma_f32_32x32x2_f32 v[18:33], v91, v191, v[18:33]
	s_waitcnt vmcnt(30)
	v_mfma_f32_32x32x2_f32 v[2:17], v92, v192, v[2:17]
	v_mfma_f32_32x32x2_f32 v[18:33], v92, v193, v[18:33]
	s_waitcnt vmcnt(28)
	v_mfma_f32_32x32x2_f32 v[2:17], v93, v194, v[2:17]
	v_mfma_f32_32x32x2_f32 v[18:33], v93, v195, v[18:33]
	s_waitcnt vmcnt(26)
	v_mfma_f32_32x32x2_f32 v[2:17], v94, v196, v[2:17]
	v_mfma_f32_32x32x2_f32 v[18:33], v94, v197, v[18:33]
	s_waitcnt vmcnt(24)
	v_mfma_f32_32x32x2_f32 v[2:17], v95, v198, v[2:17]
	v_mfma_f32_32x32x2_f32 v[18:33], v95, v199, v[18:33]
	s_waitcnt vmcnt(22)
	v_mfma_f32_32x32x2_f32 v[2:17], v96, v200, v[2:17]
	v_mfma_f32_32x32x2_f32 v[18:33], v96, v201, v[18:33]
	s_waitcnt vmcnt(20)
	v_mfma_f32_32x32x2_f32 v[2:17], v97, v202, v[2:17]
	v_mfma_f32_32x32x2_f32 v[18:33], v97, v203, v[18:33]
	s_waitcnt vmcnt(18)
	v_mfma_f32_32x32x2_f32 v[2:17], v98, v204, v[2:17]
	v_mfma_f32_32x32x2_f32 v[18:33], v98, v205, v[18:33]
	s_waitcnt vmcnt(16)
	v_mfma_f32_32x32x2_f32 v[2:17], v99, v206, v[2:17]
	v_mfma_f32_32x32x2_f32 v[18:33], v99, v207, v[18:33]
	s_waitcnt vmcnt(14)
	v_mfma_f32_32x32x2_f32 v[2:17], v100, v208, v[2:17]
	v_mfma_f32_32x32x2_f32 v[18:33], v100, v209, v[18:33]
	s_waitcnt vmcnt(12)
	v_mfma_f32_32x32x2_f32 v[2:17], v101, v210, v[2:17]
	v_mfma_f32_32x32x2_f32 v[18:33], v101, v211, v[18:33]
	s_waitcnt vmcnt(10)
	v_mfma_f32_32x32x2_f32 v[2:17], v102, v212, v[2:17]
	v_mfma_f32_32x32x2_f32 v[18:33], v102, v213, v[18:33]
	s_waitcnt vmcnt(8)
	v_mfma_f32_32x32x2_f32 v[2:17], v103, v214, v[2:17]
	v_mfma_f32_32x32x2_f32 v[18:33], v103, v215, v[18:33]
	s_waitcnt vmcnt(6)
	v_mfma_f32_32x32x2_f32 v[2:17], v104, v216, v[2:17]
	v_mfma_f32_32x32x2_f32 v[18:33], v104, v217, v[18:33]
	s_waitcnt vmcnt(4)
	v_mfma_f32_32x32x2_f32 v[2:17], v105, v218, v[2:17]
	v_mfma_f32_32x32x2_f32 v[18:33], v105, v219, v[18:33]
	s_waitcnt vmcnt(2)
	v_mfma_f32_32x32x2_f32 v[2:17], v106, v220, v[2:17]
	v_mfma_f32_32x32x2_f32 v[18:33], v106, v221, v[18:33]
	s_waitcnt vmcnt(0)
	v_mfma_f32_32x32x2_f32 v[2:17], v107, v222, v[2:17]
	v_mfma_f32_32x32x2_f32 v[18:33], v107, v223, v[18:33]
	s_nop 15
	s_nop 3
	s_barrier
	v_lshlrev_b32_e32 v115, 13, v129
	v_lshl_add_u32 v115, v109, 10, v115
	v_lshl_add_u32 v115, v108, 2, v115
	ds_write_b32 v115, v2
	ds_write_b32 v115, v3 offset:256
	ds_write_b32 v115, v4 offset:512
	ds_write_b32 v115, v5 offset:768
	ds_write_b32 v115, v6 offset:2048
	ds_write_b32 v115, v7 offset:2304
	ds_write_b32 v115, v8 offset:2560
	ds_write_b32 v115, v9 offset:2816
	ds_write_b32 v115, v10 offset:4096
	ds_write_b32 v115, v11 offset:4352
	ds_write_b32 v115, v12 offset:4608
	ds_write_b32 v115, v13 offset:4864
	ds_write_b32 v115, v14 offset:6144
	ds_write_b32 v115, v15 offset:6400
	ds_write_b32 v115, v16 offset:6656
	ds_write_b32 v115, v17 offset:6912
	ds_write_b32 v115, v18 offset:128
	ds_write_b32 v115, v19 offset:384
	ds_write_b32 v115, v20 offset:640
	ds_write_b32 v115, v21 offset:896
	ds_write_b32 v115, v22 offset:2176
	ds_write_b32 v115, v23 offset:2432
	ds_write_b32 v115, v24 offset:2688
	ds_write_b32 v115, v25 offset:2944
	ds_write_b32 v115, v26 offset:4224
	ds_write_b32 v115, v27 offset:4480
	ds_write_b32 v115, v28 offset:4736
	ds_write_b32 v115, v29 offset:4992
	ds_write_b32 v115, v30 offset:6272
	ds_write_b32 v115, v31 offset:6528
	ds_write_b32 v115, v32 offset:6784
	ds_write_b32 v115, v33 offset:7040
	v_lshl_or_b32 v2, s26, 6, v36
	v_ashrrev_i32_e32 v3, 31, v2
	v_lshl_add_u64 v[2:3], v[2:3], 2, s[18:19]
	s_mov_b64 s[16:17], 0
	v_mov_b32_e32 v4, v42
	v_mov_b32_e32 v6, v128
	s_waitcnt lgkmcnt(0)
	s_barrier
